# in-proj epilogue: rotary cos/sin rows prefetched one round ahead into alternating register sets (on top of v42)
# speedup vs baseline: 1.0036x; 1.0036x over previous
; __device__ __forceinline__ unsigned cvt_pk_bf16(float lo, float hi) { unsigned r; asm volatile("v_cvt_pk_bf16_f32 %0, %1, %2" : "=v"(r) : "v"(lo), "v"(hi)); return r; }
;     __device__ __forceinline__ void operator()(const f32x4 (&acc)[2][2][4][2], const Unit& u, int wr, int wc, int fr, int fq) const {
;     ...
;             if (rot_wave && fq < 2) {
; #pragma unroll
;                 for (int mm = 0; mm < 2; ++mm) { const float* cr = cs + (size_t)(row0 + ai * HALF + (2 * mh + mm) * 16) * 16 + 4 * fq;
;                     cc[mm][0] = *(const f32x4*)(cr); cc[mm][1] = *(const f32x4*)(cr + 8); }
;             }
; #pragma unroll
;             for (int mm = 0; mm < 2; ++mm) {
;                 const int m = 2 * mh + mm;
;                 const int row = row0 + ai * HALF + m * 16;
;                 bf16_t* rowp = O + (size_t)row * INW + col0;
; #pragma unroll
;                 for (int bj = 0; bj < 2; ++bj) {
;                     f32x4 v0 = acc[ai][bj][m][0] + bv[bj][0], v1 = acc[ai][bj][m][1] + bv[bj][1];
;                     const int cb = colt + bj * HALF;
;                     if (rot_wave && cb < 640) {
;                         const f32x4 t1 = v0, t2 = v1;
;                         v0 = t1 * cc[mm][0] - t2 * cc[mm][1]; v1 = t2 * cc[mm][0] + t1 * cc[mm][1];
;                     }
;                     if (cb < 512) { v0 = v0 * 0.125f; v1 = v1 * 0.125f; }
;                     u32x4 w; w.x = cvt_pk_bf16(v0[0], v0[1]); w.y = cvt_pk_bf16(v0[2], v0[3]); w.z = cvt_pk_bf16(v1[0], v1[1]); w.w = cvt_pk_bf16(v1[2], v1[3]);
;                     *(u32x4*)(rowp + bj * HALF) = w;
.LBB0_193:
	s_or_b64 exec, exec, s[0:1]
	s_waitcnt vmcnt(0)
	v_mov_b32_e32 v228, 1.0
	v_mov_b32_e32 v229, 1.0
	v_mov_b32_e32 v230, 1.0
	v_mov_b32_e32 v231, 1.0
	v_mov_b32_e32 v224, 1.0
	v_mov_b32_e32 v225, 1.0
	v_mov_b32_e32 v226, 1.0
	v_mov_b32_e32 v227, 1.0
	v_mov_b32_e32 v232, 0
	v_mov_b32_e32 v233, 0
	v_mov_b32_e32 v234, 0
	v_mov_b32_e32 v235, 0
	v_mov_b32_e32 v220, 0
	v_mov_b32_e32 v221, 0
	v_mov_b32_e32 v222, 0
	v_mov_b32_e32 v223, 0
	s_mov_b64 s[100:101], exec
	s_andn2_b64 exec, exec, s[58:59]
	s_cbranch_execz .Lcs_skip_r1
	v_or_b32_e32 v236, 32, v188
	v_ashrrev_i32_e32 v237, 31, v236
	v_lshlrev_b64 v[236:237], 6, v[236:237]
	v_lshl_add_u64 v[236:237], v[180:181], 0, v[236:237]
	global_load_dwordx4 v[228:231], v[236:237], off
	global_load_dwordx4 v[232:235], v[236:237], off offset:32
	v_or_b32_e32 v238, 48, v188
	v_ashrrev_i32_e32 v239, 31, v238
	v_lshlrev_b64 v[238:239], 6, v[238:239]
	v_lshl_add_u64 v[238:239], v[180:181], 0, v[238:239]
	global_load_dwordx4 v[224:227], v[238:239], off
	global_load_dwordx4 v[220:223], v[238:239], off offset:32
.Lcs_skip_r1:
	s_mov_b64 exec, s[100:101]
	v_pk_add_f32 v[140:141], v[140:141], v[92:93]
	v_pk_add_f32 v[138:139], v[138:139], v[90:91]
	v_pk_add_f32 v[144:145], v[144:145], v[96:97]
	v_pk_add_f32 v[142:143], v[142:143], v[94:95]
	v_pk_mul_f32 v[216:217], v[138:139], v[154:155]
	v_pk_mul_f32 v[218:219], v[140:141], v[156:157]
	v_pk_mul_f32 v[212:213], v[138:139], v[158:159]
	v_pk_mul_f32 v[214:215], v[140:141], v[160:161]
	v_pk_fma_f32 v[218:219], v[144:145], v[160:161], v[218:219]
	v_pk_fma_f32 v[216:217], v[142:143], v[158:159], v[216:217]
	v_pk_fma_f32 v[214:215], v[144:145], v[156:157], v[214:215] neg_lo:[0,0,1] neg_hi:[0,0,1]
	v_pk_fma_f32 v[212:213], v[142:143], v[154:155], v[212:213] neg_lo:[0,0,1] neg_hi:[0,0,1]
	v_cndmask_b32_e64 v141, v141, v219, s[40:41]
	v_cndmask_b32_e64 v140, v140, v218, s[40:41]
	v_cndmask_b32_e64 v139, v139, v217, s[40:41]
	v_cndmask_b32_e64 v138, v138, v216, s[40:41]
	s_cmp_lt_i32 s44, 2
	v_ashrrev_i32_e32 v187, 31, v186
	v_mov_b64_e32 v[208:209], s[74:75]
	v_cndmask_b32_e64 v145, v145, v215, s[40:41]
	v_cndmask_b32_e64 v144, v144, v214, s[40:41]
	v_cndmask_b32_e64 v143, v143, v213, s[40:41]
	v_cndmask_b32_e64 v142, v142, v212, s[40:41]
	v_pk_mul_f32 v[216:217], v[140:141], s[28:29] op_sel_hi:[1,0]
	v_pk_mul_f32 v[218:219], v[138:139], s[28:29] op_sel_hi:[1,0]
	s_cselect_b64 s[42:43], -1, 0
	v_mad_i64_i32 v[210:211], s[0:1], v188, s85, v[208:209]
	v_lshlrev_b64 v[186:187], 1, v[186:187]
	v_pk_mul_f32 v[212:213], v[144:145], s[28:29] op_sel_hi:[1,0]
	v_pk_mul_f32 v[214:215], v[142:143], s[28:29] op_sel_hi:[1,0]
	v_cndmask_b32_e64 v189, v140, v216, s[42:43]
	v_cndmask_b32_e64 v141, v141, v217, s[42:43]
	v_cndmask_b32_e64 v140, v138, v218, s[42:43]
	v_lshl_add_u64 v[210:211], v[210:211], 0, v[186:187]
	v_cndmask_b32_e64 v144, v144, v212, s[42:43]
	v_cndmask_b32_e64 v145, v145, v213, s[42:43]
	v_cndmask_b32_e64 v142, v142, v214, s[42:43]
	v_cndmask_b32_e64 v143, v143, v215, s[42:43]
	v_cndmask_b32_e64 v212, v139, v219, s[42:43]
	v_cvt_pk_bf16_f32 v138, v142, v143
	v_cvt_pk_bf16_f32 v139, v144, v145
	v_cvt_pk_bf16_f32 v140, v140, v212
	v_cvt_pk_bf16_f32 v141, v189, v141
	v_pk_add_f32 v[132:133], v[132:133], v[76:77]
	v_pk_add_f32 v[130:131], v[130:131], v[74:75]
	ds_bpermute_b32 v138, v248, v138
	ds_bpermute_b32 v139, v248, v139
	ds_bpermute_b32 v140, v248, v140
	ds_bpermute_b32 v141, v248, v141
	v_lshl_add_u64 v[254:255], v[210:211], 0, v[252:253]
	s_waitcnt lgkmcnt(0)
	global_store_dwordx4 v[254:255], v[138:141], off
	v_pk_add_f32 v[136:137], v[136:137], v[80:81]
	v_pk_add_f32 v[134:135], v[134:135], v[78:79]
	v_pk_mul_f32 v[138:139], v[130:131], v[158:159]
	v_pk_mul_f32 v[140:141], v[132:133], v[160:161]
	v_pk_mul_f32 v[142:143], v[130:131], v[154:155]
	v_pk_mul_f32 v[144:145], v[132:133], v[156:157]
	v_pk_fma_f32 v[140:141], v[136:137], v[156:157], v[140:141] neg_lo:[0,0,1] neg_hi:[0,0,1]
	v_pk_fma_f32 v[138:139], v[134:135], v[154:155], v[138:139] neg_lo:[0,0,1] neg_hi:[0,0,1]
	v_pk_fma_f32 v[144:145], v[136:137], v[160:161], v[144:145]
	v_pk_fma_f32 v[142:143], v[134:135], v[158:159], v[142:143]
	v_cndmask_b32_e32 v137, v137, v141, vcc
	v_cndmask_b32_e32 v136, v136, v140, vcc
	v_cndmask_b32_e32 v135, v135, v139, vcc
	v_cndmask_b32_e32 v134, v134, v138, vcc
	v_cndmask_b32_e32 v133, v133, v145, vcc
	v_cndmask_b32_e32 v132, v132, v144, vcc
	v_cndmask_b32_e32 v131, v131, v143, vcc
	v_cndmask_b32_e32 v130, v130, v142, vcc
	s_cmpk_lt_i32 s16, 0x200
	v_pk_mul_f32 v[138:139], v[136:137], s[28:29] op_sel_hi:[1,0]
	v_pk_mul_f32 v[140:141], v[134:135], s[28:29] op_sel_hi:[1,0]
	v_pk_mul_f32 v[142:143], v[132:133], s[28:29] op_sel_hi:[1,0]
	v_pk_mul_f32 v[144:145], v[130:131], s[28:29] op_sel_hi:[1,0]
	s_cselect_b64 s[44:45], -1, 0
	v_cndmask_b32_e64 v136, v136, v138, s[44:45]
	v_cndmask_b32_e64 v137, v137, v139, s[44:45]
	v_cndmask_b32_e64 v134, v134, v140, s[44:45]
	v_cndmask_b32_e64 v135, v135, v141, s[44:45]
	v_cndmask_b32_e64 v138, v132, v142, s[44:45]
	v_cndmask_b32_e64 v133, v133, v143, s[44:45]
	v_cndmask_b32_e64 v132, v130, v144, s[44:45]
	v_cndmask_b32_e64 v139, v131, v145, s[44:45]
	v_cvt_pk_bf16_f32 v130, v134, v135
	v_cvt_pk_bf16_f32 v131, v136, v137
	v_cvt_pk_bf16_f32 v132, v132, v139
	v_cvt_pk_bf16_f32 v133, v138, v133
	ds_bpermute_b32 v130, v248, v130
	ds_bpermute_b32 v131, v248, v131
	ds_bpermute_b32 v132, v248, v132
	ds_bpermute_b32 v133, v248, v133
	v_lshl_add_u64 v[254:255], v[210:211], 0, v[252:253]
	s_waitcnt lgkmcnt(0)
; __device__ __forceinline__ unsigned cvt_pk_bf16(float lo, float hi) { unsigned r; asm volatile("v_cvt_pk_bf16_f32 %0, %1, %2" : "=v"(r) : "v"(lo), "v"(hi)); return r; }
;     __device__ __forceinline__ void operator()(const f32x4 (&acc)[2][2][4][2], const Unit& u, int wr, int wc, int fr, int fq) const {
;     ...
;             if (rot_wave && fq < 2) {
; #pragma unroll
;                 for (int mm = 0; mm < 2; ++mm) { const float* cr = cs + (size_t)(row0 + ai * HALF + (2 * mh + mm) * 16) * 16 + 4 * fq;
;                     cc[mm][0] = *(const f32x4*)(cr); cc[mm][1] = *(const f32x4*)(cr + 8); }
;             }
; #pragma unroll
;             for (int mm = 0; mm < 2; ++mm) {
;                 const int m = 2 * mh + mm;
;                 const int row = row0 + ai * HALF + m * 16;
;                 bf16_t* rowp = O + (size_t)row * INW + col0;
; #pragma unroll
;                 for (int bj = 0; bj < 2; ++bj) {
;                     f32x4 v0 = acc[ai][bj][m][0] + bv[bj][0], v1 = acc[ai][bj][m][1] + bv[bj][1];
;                     const int cb = colt + bj * HALF;
;                     if (rot_wave && cb < 640) {
;                         const f32x4 t1 = v0, t2 = v1;
;                         v0 = t1 * cc[mm][0] - t2 * cc[mm][1]; v1 = t2 * cc[mm][0] + t1 * cc[mm][1];
;                     }
;                     if (cb < 512) { v0 = v0 * 0.125f; v1 = v1 * 0.125f; }
;                     u32x4 w; w.x = cvt_pk_bf16(v0[0], v0[1]); w.y = cvt_pk_bf16(v0[2], v0[3]); w.z = cvt_pk_bf16(v1[0], v1[1]); w.w = cvt_pk_bf16(v1[2], v1[3]);
;                     *(u32x4*)(rowp + bj * HALF) = w;
	global_store_dwordx4 v[254:255], v[130:133], off offset:256
	v_pk_add_f32 v[124:125], v[124:125], v[92:93]
	v_pk_add_f32 v[122:123], v[122:123], v[90:91]
	v_mad_u64_u32 v[130:131], s[0:1], v190, s85, v[208:209]
	v_mov_b32_e32 v132, v131
	v_mad_u64_u32 v[132:133], s[0:1], v191, s85, v[132:133]
	v_pk_add_f32 v[128:129], v[128:129], v[96:97]
	v_pk_add_f32 v[126:127], v[126:127], v[94:95]
	v_pk_mul_f32 v[134:135], v[124:125], v[148:149]
	v_pk_mul_f32 v[136:137], v[122:123], v[150:151]
	v_pk_mul_f32 v[138:139], v[124:125], v[152:153]
	v_mov_b32_e32 v131, v132
	v_pk_mul_f32 v[132:133], v[122:123], v[146:147]
	v_pk_fma_f32 v[134:135], v[128:129], v[152:153], v[134:135] neg_lo:[0,0,1] neg_hi:[0,0,1]
	v_pk_fma_f32 v[138:139], v[128:129], v[148:149], v[138:139]
	v_pk_fma_f32 v[136:137], v[126:127], v[146:147], v[136:137]
	v_pk_fma_f32 v[132:133], v[126:127], v[150:151], v[132:133] neg_lo:[0,0,1] neg_hi:[0,0,1]
	v_cndmask_b32_e64 v129, v129, v135, s[40:41]
	v_cndmask_b32_e64 v128, v128, v134, s[40:41]
	v_cndmask_b32_e64 v125, v125, v139, s[40:41]
	v_cndmask_b32_e64 v124, v124, v138, s[40:41]
	v_cndmask_b32_e64 v123, v123, v137, s[40:41]
	v_cndmask_b32_e64 v122, v122, v136, s[40:41]
	v_cndmask_b32_e64 v127, v127, v133, s[40:41]
	v_cndmask_b32_e64 v126, v126, v132, s[40:41]
	v_pk_mul_f32 v[132:133], v[128:129], s[28:29] op_sel_hi:[1,0]
	v_pk_mul_f32 v[136:137], v[124:125], s[28:29] op_sel_hi:[1,0]
	v_pk_mul_f32 v[138:139], v[122:123], s[28:29] op_sel_hi:[1,0]
	v_pk_mul_f32 v[134:135], v[126:127], s[28:29] op_sel_hi:[1,0]
	v_cndmask_b32_e64 v128, v128, v132, s[42:43]
	v_cndmask_b32_e64 v132, v124, v136, s[42:43]
	v_cndmask_b32_e64 v125, v125, v137, s[42:43]
	v_cndmask_b32_e64 v124, v122, v138, s[42:43]
	v_lshl_add_u64 v[130:131], v[130:131], 0, v[186:187]
	v_cndmask_b32_e64 v129, v129, v133, s[42:43]
	v_cndmask_b32_e64 v126, v126, v134, s[42:43]
	v_cndmask_b32_e64 v127, v127, v135, s[42:43]
	v_cndmask_b32_e64 v133, v123, v139, s[42:43]
	v_cvt_pk_bf16_f32 v122, v126, v127
	v_cvt_pk_bf16_f32 v123, v128, v129
	v_cvt_pk_bf16_f32 v124, v124, v133
	v_cvt_pk_bf16_f32 v125, v132, v125
	v_pk_add_f32 v[116:117], v[116:117], v[76:77]
	v_pk_add_f32 v[114:115], v[114:115], v[74:75]
	ds_bpermute_b32 v122, v248, v122
	ds_bpermute_b32 v123, v248, v123
	ds_bpermute_b32 v124, v248, v124
	ds_bpermute_b32 v125, v248, v125
	v_lshl_add_u64 v[254:255], v[130:131], 0, v[252:253]
	s_waitcnt lgkmcnt(0)
	global_store_dwordx4 v[254:255], v[122:125], off
	v_pk_add_f32 v[120:121], v[120:121], v[80:81]
	v_pk_add_f32 v[118:119], v[118:119], v[78:79]
	v_pk_mul_f32 v[124:125], v[116:117], v[148:149]
	v_pk_mul_f32 v[126:127], v[114:115], v[150:151]
	v_pk_mul_f32 v[128:129], v[116:117], v[152:153]
	v_pk_mul_f32 v[122:123], v[114:115], v[146:147]
	v_pk_fma_f32 v[124:125], v[120:121], v[152:153], v[124:125] neg_lo:[0,0,1] neg_hi:[0,0,1]
	v_pk_fma_f32 v[128:129], v[120:121], v[148:149], v[128:129]
	v_pk_fma_f32 v[126:127], v[118:119], v[146:147], v[126:127]
	v_pk_fma_f32 v[122:123], v[118:119], v[150:151], v[122:123] neg_lo:[0,0,1] neg_hi:[0,0,1]
	v_cndmask_b32_e32 v121, v121, v125, vcc
	v_cndmask_b32_e32 v120, v120, v124, vcc
	v_cndmask_b32_e32 v117, v117, v129, vcc
	v_cndmask_b32_e32 v116, v116, v128, vcc
	v_cndmask_b32_e32 v115, v115, v127, vcc
	v_cndmask_b32_e32 v114, v114, v126, vcc
	v_cndmask_b32_e32 v119, v119, v123, vcc
	v_cndmask_b32_e32 v118, v118, v122, vcc
	v_pk_mul_f32 v[122:123], v[120:121], s[28:29] op_sel_hi:[1,0]
	v_pk_mul_f32 v[126:127], v[116:117], s[28:29] op_sel_hi:[1,0]
	v_pk_mul_f32 v[128:129], v[114:115], s[28:29] op_sel_hi:[1,0]
	v_pk_mul_f32 v[124:125], v[118:119], s[28:29] op_sel_hi:[1,0]
	v_cndmask_b32_e64 v120, v120, v122, s[44:45]
	v_cndmask_b32_e64 v122, v116, v126, s[44:45]
	v_cndmask_b32_e64 v117, v117, v127, s[44:45]
	v_cndmask_b32_e64 v116, v114, v128, s[44:45]
	v_cndmask_b32_e64 v121, v121, v123, s[44:45]
	v_cndmask_b32_e64 v118, v118, v124, s[44:45]
	v_cndmask_b32_e64 v119, v119, v125, s[44:45]
	v_cndmask_b32_e64 v123, v115, v129, s[44:45]
	v_cvt_pk_bf16_f32 v114, v118, v119
	v_cvt_pk_bf16_f32 v115, v120, v121
	v_cvt_pk_bf16_f32 v116, v116, v123
	v_cvt_pk_bf16_f32 v117, v122, v117
	ds_bpermute_b32 v114, v248, v114
	ds_bpermute_b32 v115, v248, v115
	ds_bpermute_b32 v116, v248, v116
	ds_bpermute_b32 v117, v248, v117
	v_lshl_add_u64 v[254:255], v[130:131], 0, v[252:253]
	s_waitcnt lgkmcnt(0)
	global_store_dwordx4 v[254:255], v[114:117], off offset:256
	v_or_b32_e32 v130, 48, v188
	v_ashrrev_i32_e32 v131, 31, v130
	v_or_b32_e32 v132, 32, v188
	v_ashrrev_i32_e32 v133, 31, v132
	v_pk_add_f32 v[108:109], v[108:109], v[92:93]
	v_pk_add_f32 v[106:107], v[106:107], v[90:91]
	v_pk_add_f32 v[112:113], v[112:113], v[96:97]
	v_pk_add_f32 v[110:111], v[110:111], v[94:95]
	s_waitcnt vmcnt(4)
	v_mov_b32_e32 v154, 1.0
	v_mov_b32_e32 v155, 1.0
	v_mov_b32_e32 v156, 1.0
	v_mov_b32_e32 v157, 1.0
	v_mov_b32_e32 v150, 1.0
	v_mov_b32_e32 v151, 1.0
	v_mov_b32_e32 v152, 1.0
	v_mov_b32_e32 v153, 1.0
	v_mov_b32_e32 v158, 0
	v_mov_b32_e32 v159, 0
	v_mov_b32_e32 v160, 0
	v_mov_b32_e32 v161, 0
	v_mov_b32_e32 v146, 0
	v_mov_b32_e32 v147, 0
	v_mov_b32_e32 v148, 0
	v_mov_b32_e32 v149, 0
	s_mov_b64 s[100:101], exec
	s_andn2_b64 exec, exec, s[58:59]
	s_cbranch_execz .Lcs_skip_r2
	v_add_u32_e32 v236, 0x80, v188
	v_ashrrev_i32_e32 v237, 31, v236
	v_lshlrev_b64 v[236:237], 6, v[236:237]
	v_lshl_add_u64 v[236:237], v[180:181], 0, v[236:237]
	global_load_dwordx4 v[154:157], v[236:237], off
	global_load_dwordx4 v[158:161], v[236:237], off offset:32
	v_add_u32_e32 v238, 0x90, v188
	v_ashrrev_i32_e32 v239, 31, v238
	v_lshlrev_b64 v[238:239], 6, v[238:239]
	v_lshl_add_u64 v[238:239], v[180:181], 0, v[238:239]
	global_load_dwordx4 v[150:153], v[238:239], off
	global_load_dwordx4 v[146:149], v[238:239], off offset:32
; __device__ __forceinline__ unsigned cvt_pk_bf16(float lo, float hi) { unsigned r; asm volatile("v_cvt_pk_bf16_f32 %0, %1, %2" : "=v"(r) : "v"(lo), "v"(hi)); return r; }
;     __device__ __forceinline__ void operator()(const f32x4 (&acc)[2][2][4][2], const Unit& u, int wr, int wc, int fr, int fq) const {
;     ...
;             if (rot_wave && fq < 2) {
; #pragma unroll
;                 for (int mm = 0; mm < 2; ++mm) { const float* cr = cs + (size_t)(row0 + ai * HALF + (2 * mh + mm) * 16) * 16 + 4 * fq;
;                     cc[mm][0] = *(const f32x4*)(cr); cc[mm][1] = *(const f32x4*)(cr + 8); }
;             }
; #pragma unroll
;             for (int mm = 0; mm < 2; ++mm) {
;                 const int m = 2 * mh + mm;
;                 const int row = row0 + ai * HALF + m * 16;
;                 bf16_t* rowp = O + (size_t)row * INW + col0;
; #pragma unroll
;                 for (int bj = 0; bj < 2; ++bj) {
;                     f32x4 v0 = acc[ai][bj][m][0] + bv[bj][0], v1 = acc[ai][bj][m][1] + bv[bj][1];
;                     const int cb = colt + bj * HALF;
;                     if (rot_wave && cb < 640) {
;                         const f32x4 t1 = v0, t2 = v1;
;                         v0 = t1 * cc[mm][0] - t2 * cc[mm][1]; v1 = t2 * cc[mm][0] + t1 * cc[mm][1];
;                     }
;                     if (cb < 512) { v0 = v0 * 0.125f; v1 = v1 * 0.125f; }
;                     u32x4 w; w.x = cvt_pk_bf16(v0[0], v0[1]); w.y = cvt_pk_bf16(v0[2], v0[3]); w.z = cvt_pk_bf16(v1[0], v1[1]); w.w = cvt_pk_bf16(v1[2], v1[3]);
;                     *(u32x4*)(rowp + bj * HALF) = w;
.Lcs_skip_r2:
	s_mov_b64 exec, s[100:101]
	v_pk_mul_f32 v[138:139], v[108:109], v[234:235]
	v_pk_mul_f32 v[140:141], v[106:107], v[228:229]
	v_pk_mul_f32 v[142:143], v[108:109], v[230:231]
	v_pk_mul_f32 v[136:137], v[106:107], v[232:233]
	v_pk_fma_f32 v[138:139], v[112:113], v[230:231], v[138:139] neg_lo:[0,0,1] neg_hi:[0,0,1]
	v_pk_fma_f32 v[142:143], v[112:113], v[234:235], v[142:143]
	v_pk_fma_f32 v[140:141], v[110:111], v[232:233], v[140:141]
	v_pk_fma_f32 v[136:137], v[110:111], v[228:229], v[136:137] neg_lo:[0,0,1] neg_hi:[0,0,1]
	v_cndmask_b32_e64 v113, v113, v139, s[40:41]
	v_cndmask_b32_e64 v112, v112, v138, s[40:41]
	v_cndmask_b32_e64 v109, v109, v143, s[40:41]
	v_cndmask_b32_e64 v108, v108, v142, s[40:41]
	v_cndmask_b32_e64 v107, v107, v141, s[40:41]
	v_cndmask_b32_e64 v106, v106, v140, s[40:41]
	v_mov_b64_e32 v[134:135], s[74:75]
	v_cndmask_b32_e64 v111, v111, v137, s[40:41]
	v_cndmask_b32_e64 v110, v110, v136, s[40:41]
	v_pk_mul_f32 v[136:137], v[112:113], s[28:29] op_sel_hi:[1,0]
	v_pk_mul_f32 v[140:141], v[108:109], s[28:29] op_sel_hi:[1,0]
	v_pk_mul_f32 v[142:143], v[106:107], s[28:29] op_sel_hi:[1,0]
	v_mad_i64_i32 v[132:133], s[0:1], v132, s85, v[134:135]
	v_pk_mul_f32 v[138:139], v[110:111], s[28:29] op_sel_hi:[1,0]
	v_cndmask_b32_e64 v112, v112, v136, s[42:43]
	v_cndmask_b32_e64 v136, v108, v140, s[42:43]
	v_cndmask_b32_e64 v109, v109, v141, s[42:43]
	v_cndmask_b32_e64 v108, v106, v142, s[42:43]
	v_lshl_add_u64 v[132:133], v[132:133], 0, v[186:187]
	v_cndmask_b32_e64 v113, v113, v137, s[42:43]
	v_cndmask_b32_e64 v110, v110, v138, s[42:43]
	v_cndmask_b32_e64 v111, v111, v139, s[42:43]
	v_cndmask_b32_e64 v137, v107, v143, s[42:43]
	v_cvt_pk_bf16_f32 v106, v110, v111
	v_cvt_pk_bf16_f32 v107, v112, v113
	v_cvt_pk_bf16_f32 v108, v108, v137
	v_cvt_pk_bf16_f32 v109, v136, v109
	v_pk_add_f32 v[100:101], v[100:101], v[76:77]
	v_pk_add_f32 v[98:99], v[98:99], v[74:75]
	ds_bpermute_b32 v106, v248, v106
	ds_bpermute_b32 v107, v248, v107
	ds_bpermute_b32 v108, v248, v108
	ds_bpermute_b32 v109, v248, v109
	v_lshl_add_u64 v[254:255], v[132:133], 0, v[252:253]
	s_waitcnt lgkmcnt(0)
	global_store_dwordx4 v[254:255], v[106:109], off
	v_pk_add_f32 v[104:105], v[104:105], v[80:81]
	v_pk_add_f32 v[102:103], v[102:103], v[78:79]
	v_pk_mul_f32 v[106:107], v[98:99], v[232:233]
	v_pk_mul_f32 v[108:109], v[100:101], v[234:235]
	v_pk_mul_f32 v[110:111], v[98:99], v[228:229]
	v_pk_mul_f32 v[112:113], v[100:101], v[230:231]
	v_pk_fma_f32 v[108:109], v[104:105], v[230:231], v[108:109] neg_lo:[0,0,1] neg_hi:[0,0,1]
	v_pk_fma_f32 v[106:107], v[102:103], v[228:229], v[106:107] neg_lo:[0,0,1] neg_hi:[0,0,1]
	v_pk_fma_f32 v[112:113], v[104:105], v[234:235], v[112:113]
	v_pk_fma_f32 v[110:111], v[102:103], v[232:233], v[110:111]
	v_cndmask_b32_e32 v105, v105, v109, vcc
	v_cndmask_b32_e32 v104, v104, v108, vcc
	v_cndmask_b32_e32 v103, v103, v107, vcc
	v_cndmask_b32_e32 v102, v102, v106, vcc
	v_cndmask_b32_e32 v101, v101, v113, vcc
	v_cndmask_b32_e32 v100, v100, v112, vcc
	v_cndmask_b32_e32 v99, v99, v111, vcc
	v_cndmask_b32_e32 v98, v98, v110, vcc
	v_pk_mul_f32 v[106:107], v[104:105], s[28:29] op_sel_hi:[1,0]
	v_pk_mul_f32 v[108:109], v[102:103], s[28:29] op_sel_hi:[1,0]
	v_pk_mul_f32 v[110:111], v[100:101], s[28:29] op_sel_hi:[1,0]
	v_pk_mul_f32 v[112:113], v[98:99], s[28:29] op_sel_hi:[1,0]
	v_cndmask_b32_e64 v104, v104, v106, s[44:45]
	v_cndmask_b32_e64 v105, v105, v107, s[44:45]
	v_cndmask_b32_e64 v102, v102, v108, s[44:45]
	v_cndmask_b32_e64 v103, v103, v109, s[44:45]
	v_cndmask_b32_e64 v106, v100, v110, s[44:45]
	v_cndmask_b32_e64 v101, v101, v111, s[44:45]
	v_cndmask_b32_e64 v100, v98, v112, s[44:45]
	v_cndmask_b32_e64 v107, v99, v113, s[44:45]
	v_cvt_pk_bf16_f32 v98, v102, v103
	v_cvt_pk_bf16_f32 v99, v104, v105
	v_cvt_pk_bf16_f32 v100, v100, v107
	v_cvt_pk_bf16_f32 v101, v106, v101
	ds_bpermute_b32 v98, v248, v98
	ds_bpermute_b32 v99, v248, v99
	ds_bpermute_b32 v100, v248, v100
	ds_bpermute_b32 v101, v248, v101
	v_lshl_add_u64 v[254:255], v[132:133], 0, v[252:253]
	s_waitcnt lgkmcnt(0)
	global_store_dwordx4 v[254:255], v[98:101], off offset:256
	v_pk_add_f32 v[84:85], v[84:85], v[92:93]
	v_pk_add_f32 v[82:83], v[82:83], v[90:91]
	v_mad_u64_u32 v[98:99], s[0:1], v130, s85, v[134:135]
	v_mov_b32_e32 v100, v99
	v_mad_u64_u32 v[100:101], s[0:1], v131, s85, v[100:101]
	v_pk_add_f32 v[88:89], v[88:89], v[96:97]
	v_pk_add_f32 v[86:87], v[86:87], v[94:95]
	v_pk_mul_f32 v[102:103], v[84:85], v[222:223]
	v_pk_mul_f32 v[104:105], v[82:83], v[224:225]
	v_pk_mul_f32 v[106:107], v[84:85], v[226:227]
	v_mov_b32_e32 v99, v100
	v_pk_mul_f32 v[100:101], v[82:83], v[220:221]
	v_pk_fma_f32 v[102:103], v[88:89], v[226:227], v[102:103] neg_lo:[0,0,1] neg_hi:[0,0,1]
	v_pk_fma_f32 v[106:107], v[88:89], v[222:223], v[106:107]
	v_pk_fma_f32 v[104:105], v[86:87], v[220:221], v[104:105]
	v_pk_fma_f32 v[100:101], v[86:87], v[224:225], v[100:101] neg_lo:[0,0,1] neg_hi:[0,0,1]
	v_cndmask_b32_e64 v89, v89, v103, s[40:41]
	v_cndmask_b32_e64 v88, v88, v102, s[40:41]
	v_cndmask_b32_e64 v85, v85, v107, s[40:41]
	v_cndmask_b32_e64 v84, v84, v106, s[40:41]
	v_cndmask_b32_e64 v83, v83, v105, s[40:41]
	v_cndmask_b32_e64 v82, v82, v104, s[40:41]
	v_cndmask_b32_e64 v87, v87, v101, s[40:41]
	v_cndmask_b32_e64 v86, v86, v100, s[40:41]
	v_pk_mul_f32 v[100:101], v[88:89], s[28:29] op_sel_hi:[1,0]
	v_pk_mul_f32 v[104:105], v[84:85], s[28:29] op_sel_hi:[1,0]
	v_pk_mul_f32 v[106:107], v[82:83], s[28:29] op_sel_hi:[1,0]
	v_pk_mul_f32 v[102:103], v[86:87], s[28:29] op_sel_hi:[1,0]
	v_cndmask_b32_e64 v88, v88, v100, s[42:43]
	v_cndmask_b32_e64 v100, v84, v104, s[42:43]
	v_cndmask_b32_e64 v85, v85, v105, s[42:43]
	v_cndmask_b32_e64 v84, v82, v106, s[42:43]
	v_lshl_add_u64 v[98:99], v[98:99], 0, v[186:187]
	v_cndmask_b32_e64 v89, v89, v101, s[42:43]
	v_cndmask_b32_e64 v86, v86, v102, s[42:43]
	v_cndmask_b32_e64 v87, v87, v103, s[42:43]
	v_cndmask_b32_e64 v101, v83, v107, s[42:43]
	v_cvt_pk_bf16_f32 v82, v86, v87
	v_cvt_pk_bf16_f32 v83, v88, v89
	v_cvt_pk_bf16_f32 v84, v84, v101
	v_cvt_pk_bf16_f32 v85, v100, v85
	v_pk_add_f32 v[68:69], v[68:69], v[76:77]
	v_pk_add_f32 v[66:67], v[66:67], v[74:75]
	ds_bpermute_b32 v82, v248, v82
	ds_bpermute_b32 v83, v248, v83
	ds_bpermute_b32 v84, v248, v84
	ds_bpermute_b32 v85, v248, v85
	v_lshl_add_u64 v[254:255], v[98:99], 0, v[252:253]
	s_waitcnt lgkmcnt(0)
; __device__ __forceinline__ unsigned cvt_pk_bf16(float lo, float hi) { unsigned r; asm volatile("v_cvt_pk_bf16_f32 %0, %1, %2" : "=v"(r) : "v"(lo), "v"(hi)); return r; }
;     __device__ __forceinline__ void operator()(const f32x4 (&acc)[2][2][4][2], const Unit& u, int wr, int wc, int fr, int fq) const {
;     ...
;             if (rot_wave && fq < 2) {
; #pragma unroll
;                 for (int mm = 0; mm < 2; ++mm) { const float* cr = cs + (size_t)(row0 + ai * HALF + (2 * mh + mm) * 16) * 16 + 4 * fq;
;                     cc[mm][0] = *(const f32x4*)(cr); cc[mm][1] = *(const f32x4*)(cr + 8); }
;             }
; #pragma unroll
;             for (int mm = 0; mm < 2; ++mm) {
;                 const int m = 2 * mh + mm;
;                 const int row = row0 + ai * HALF + m * 16;
;                 bf16_t* rowp = O + (size_t)row * INW + col0;
; #pragma unroll
;                 for (int bj = 0; bj < 2; ++bj) {
;                     f32x4 v0 = acc[ai][bj][m][0] + bv[bj][0], v1 = acc[ai][bj][m][1] + bv[bj][1];
;                     const int cb = colt + bj * HALF;
;                     if (rot_wave && cb < 640) {
;                         const f32x4 t1 = v0, t2 = v1;
;                         v0 = t1 * cc[mm][0] - t2 * cc[mm][1]; v1 = t2 * cc[mm][0] + t1 * cc[mm][1];
;                     }
;                     if (cb < 512) { v0 = v0 * 0.125f; v1 = v1 * 0.125f; }
;                     u32x4 w; w.x = cvt_pk_bf16(v0[0], v0[1]); w.y = cvt_pk_bf16(v0[2], v0[3]); w.z = cvt_pk_bf16(v1[0], v1[1]); w.w = cvt_pk_bf16(v1[2], v1[3]);
;                     *(u32x4*)(rowp + bj * HALF) = w;
	global_store_dwordx4 v[254:255], v[82:85], off
	v_pk_add_f32 v[72:73], v[72:73], v[80:81]
	v_pk_add_f32 v[70:71], v[70:71], v[78:79]
	v_pk_mul_f32 v[84:85], v[68:69], v[222:223]
	v_pk_mul_f32 v[86:87], v[66:67], v[224:225]
	v_pk_mul_f32 v[88:89], v[68:69], v[226:227]
	v_pk_mul_f32 v[82:83], v[66:67], v[220:221]
	v_pk_fma_f32 v[84:85], v[72:73], v[226:227], v[84:85] neg_lo:[0,0,1] neg_hi:[0,0,1]
	v_pk_fma_f32 v[88:89], v[72:73], v[222:223], v[88:89]
	v_pk_fma_f32 v[86:87], v[70:71], v[220:221], v[86:87]
	v_pk_fma_f32 v[82:83], v[70:71], v[224:225], v[82:83] neg_lo:[0,0,1] neg_hi:[0,0,1]
	v_cndmask_b32_e32 v73, v73, v85, vcc
	v_cndmask_b32_e32 v72, v72, v84, vcc
	v_cndmask_b32_e32 v69, v69, v89, vcc
	v_cndmask_b32_e32 v68, v68, v88, vcc
	v_cndmask_b32_e32 v67, v67, v87, vcc
	v_cndmask_b32_e32 v66, v66, v86, vcc
	v_cndmask_b32_e32 v71, v71, v83, vcc
	v_cndmask_b32_e32 v70, v70, v82, vcc
	v_pk_mul_f32 v[82:83], v[72:73], s[28:29] op_sel_hi:[1,0]
	v_pk_mul_f32 v[86:87], v[68:69], s[28:29] op_sel_hi:[1,0]
	v_pk_mul_f32 v[88:89], v[66:67], s[28:29] op_sel_hi:[1,0]
	v_pk_mul_f32 v[84:85], v[70:71], s[28:29] op_sel_hi:[1,0]
	v_cndmask_b32_e64 v72, v72, v82, s[44:45]
	v_cndmask_b32_e64 v82, v68, v86, s[44:45]
	v_cndmask_b32_e64 v69, v69, v87, s[44:45]
	v_cndmask_b32_e64 v68, v66, v88, s[44:45]
	v_cndmask_b32_e64 v73, v73, v83, s[44:45]
	v_cndmask_b32_e64 v70, v70, v84, s[44:45]
	v_cndmask_b32_e64 v71, v71, v85, s[44:45]
	v_cndmask_b32_e64 v83, v67, v89, s[44:45]
	v_cvt_pk_bf16_f32 v66, v70, v71
	v_cvt_pk_bf16_f32 v67, v72, v73
	v_cvt_pk_bf16_f32 v68, v68, v83
	v_cvt_pk_bf16_f32 v69, v82, v69
	ds_bpermute_b32 v66, v248, v66
	ds_bpermute_b32 v67, v248, v67
	ds_bpermute_b32 v68, v248, v68
	ds_bpermute_b32 v69, v248, v69
	v_lshl_add_u64 v[254:255], v[98:99], 0, v[252:253]
	s_waitcnt lgkmcnt(0)
	global_store_dwordx4 v[254:255], v[66:69], off offset:256
	v_add_u32_e32 v98, 0x90, v188
	v_ashrrev_i32_e32 v99, 31, v98
	v_add_u32_e32 v100, 0x80, v188
	v_ashrrev_i32_e32 v101, 31, v100
	v_pk_add_f32 v[60:61], v[60:61], v[92:93]
	v_pk_add_f32 v[58:59], v[58:59], v[90:91]
	v_pk_add_f32 v[64:65], v[64:65], v[96:97]
	v_pk_add_f32 v[62:63], v[62:63], v[94:95]
	s_waitcnt vmcnt(4)
	v_mov_b32_e32 v228, 1.0
	v_mov_b32_e32 v229, 1.0
	v_mov_b32_e32 v230, 1.0
	v_mov_b32_e32 v231, 1.0
	v_mov_b32_e32 v224, 1.0
	v_mov_b32_e32 v225, 1.0
	v_mov_b32_e32 v226, 1.0
	v_mov_b32_e32 v227, 1.0
	v_mov_b32_e32 v232, 0
	v_mov_b32_e32 v233, 0
	v_mov_b32_e32 v234, 0
	v_mov_b32_e32 v235, 0
	v_mov_b32_e32 v220, 0
	v_mov_b32_e32 v221, 0
	v_mov_b32_e32 v222, 0
	v_mov_b32_e32 v223, 0
	s_mov_b64 s[100:101], exec
	s_andn2_b64 exec, exec, s[58:59]
	s_cbranch_execz .Lcs_skip_r3
	v_add_u32_e32 v236, 0xa0, v188
	v_ashrrev_i32_e32 v237, 31, v236
	v_lshlrev_b64 v[236:237], 6, v[236:237]
	v_lshl_add_u64 v[236:237], v[180:181], 0, v[236:237]
	global_load_dwordx4 v[228:231], v[236:237], off
	global_load_dwordx4 v[232:235], v[236:237], off offset:32
	v_add_u32_e32 v238, 0xb0, v188
	v_ashrrev_i32_e32 v239, 31, v238
	v_lshlrev_b64 v[238:239], 6, v[238:239]
	v_lshl_add_u64 v[238:239], v[180:181], 0, v[238:239]
	global_load_dwordx4 v[224:227], v[238:239], off
	global_load_dwordx4 v[220:223], v[238:239], off offset:32
.Lcs_skip_r3:
	s_mov_b64 exec, s[100:101]
	v_pk_mul_f32 v[106:107], v[60:61], v[160:161]
	v_pk_mul_f32 v[108:109], v[58:59], v[154:155]
	v_pk_mul_f32 v[110:111], v[60:61], v[156:157]
	v_pk_mul_f32 v[104:105], v[58:59], v[158:159]
	v_pk_fma_f32 v[106:107], v[64:65], v[156:157], v[106:107] neg_lo:[0,0,1] neg_hi:[0,0,1]
	v_pk_fma_f32 v[110:111], v[64:65], v[160:161], v[110:111]
	v_pk_fma_f32 v[108:109], v[62:63], v[158:159], v[108:109]
	v_pk_fma_f32 v[104:105], v[62:63], v[154:155], v[104:105] neg_lo:[0,0,1] neg_hi:[0,0,1]
	v_cndmask_b32_e64 v65, v65, v107, s[40:41]
	v_cndmask_b32_e64 v64, v64, v106, s[40:41]
	v_cndmask_b32_e64 v61, v61, v111, s[40:41]
	v_cndmask_b32_e64 v60, v60, v110, s[40:41]
	v_cndmask_b32_e64 v59, v59, v109, s[40:41]
	v_cndmask_b32_e64 v58, v58, v108, s[40:41]
	v_mov_b64_e32 v[102:103], s[74:75]
	v_cndmask_b32_e64 v63, v63, v105, s[40:41]
	v_cndmask_b32_e64 v62, v62, v104, s[40:41]
	v_pk_mul_f32 v[104:105], v[64:65], s[28:29] op_sel_hi:[1,0]
	v_pk_mul_f32 v[108:109], v[60:61], s[28:29] op_sel_hi:[1,0]
	v_pk_mul_f32 v[110:111], v[58:59], s[28:29] op_sel_hi:[1,0]
	v_mad_i64_i32 v[100:101], s[0:1], v100, s85, v[102:103]
	v_pk_mul_f32 v[106:107], v[62:63], s[28:29] op_sel_hi:[1,0]
	v_cndmask_b32_e64 v64, v64, v104, s[42:43]
	v_cndmask_b32_e64 v104, v60, v108, s[42:43]
	v_cndmask_b32_e64 v61, v61, v109, s[42:43]
	v_cndmask_b32_e64 v60, v58, v110, s[42:43]
	v_lshl_add_u64 v[100:101], v[100:101], 0, v[186:187]
	v_cndmask_b32_e64 v65, v65, v105, s[42:43]
	v_cndmask_b32_e64 v62, v62, v106, s[42:43]
	v_cndmask_b32_e64 v63, v63, v107, s[42:43]
	v_cndmask_b32_e64 v105, v59, v111, s[42:43]
	v_cvt_pk_bf16_f32 v58, v62, v63
	v_cvt_pk_bf16_f32 v59, v64, v65
	v_cvt_pk_bf16_f32 v60, v60, v105
	v_cvt_pk_bf16_f32 v61, v104, v61
	v_pk_add_f32 v[52:53], v[52:53], v[76:77]
	v_pk_add_f32 v[50:51], v[50:51], v[74:75]
	ds_bpermute_b32 v58, v248, v58
	ds_bpermute_b32 v59, v248, v59
	ds_bpermute_b32 v60, v248, v60
	ds_bpermute_b32 v61, v248, v61
	v_lshl_add_u64 v[254:255], v[100:101], 0, v[252:253]
	s_waitcnt lgkmcnt(0)
; __device__ __forceinline__ unsigned cvt_pk_bf16(float lo, float hi) { unsigned r; asm volatile("v_cvt_pk_bf16_f32 %0, %1, %2" : "=v"(r) : "v"(lo), "v"(hi)); return r; }
;     __device__ __forceinline__ void operator()(const f32x4 (&acc)[2][2][4][2], const Unit& u, int wr, int wc, int fr, int fq) const {
;     ...
;             if (rot_wave && fq < 2) {
; #pragma unroll
;                 for (int mm = 0; mm < 2; ++mm) { const float* cr = cs + (size_t)(row0 + ai * HALF + (2 * mh + mm) * 16) * 16 + 4 * fq;
;                     cc[mm][0] = *(const f32x4*)(cr); cc[mm][1] = *(const f32x4*)(cr + 8); }
;             }
; #pragma unroll
;             for (int mm = 0; mm < 2; ++mm) {
;                 const int m = 2 * mh + mm;
;                 const int row = row0 + ai * HALF + m * 16;
;                 bf16_t* rowp = O + (size_t)row * INW + col0;
; #pragma unroll
;                 for (int bj = 0; bj < 2; ++bj) {
;                     f32x4 v0 = acc[ai][bj][m][0] + bv[bj][0], v1 = acc[ai][bj][m][1] + bv[bj][1];
;                     const int cb = colt + bj * HALF;
;                     if (rot_wave && cb < 640) {
;                         const f32x4 t1 = v0, t2 = v1;
;                         v0 = t1 * cc[mm][0] - t2 * cc[mm][1]; v1 = t2 * cc[mm][0] + t1 * cc[mm][1];
;                     }
;                     if (cb < 512) { v0 = v0 * 0.125f; v1 = v1 * 0.125f; }
;                     u32x4 w; w.x = cvt_pk_bf16(v0[0], v0[1]); w.y = cvt_pk_bf16(v0[2], v0[3]); w.z = cvt_pk_bf16(v1[0], v1[1]); w.w = cvt_pk_bf16(v1[2], v1[3]);
;                     *(u32x4*)(rowp + bj * HALF) = w;
	global_store_dwordx4 v[254:255], v[58:61], off
	v_pk_add_f32 v[56:57], v[56:57], v[80:81]
	v_pk_add_f32 v[54:55], v[54:55], v[78:79]
	v_pk_mul_f32 v[58:59], v[50:51], v[158:159]
	v_pk_mul_f32 v[60:61], v[52:53], v[160:161]
	v_pk_mul_f32 v[62:63], v[50:51], v[154:155]
	v_pk_mul_f32 v[64:65], v[52:53], v[156:157]
	v_pk_fma_f32 v[60:61], v[56:57], v[156:157], v[60:61] neg_lo:[0,0,1] neg_hi:[0,0,1]
	v_pk_fma_f32 v[58:59], v[54:55], v[154:155], v[58:59] neg_lo:[0,0,1] neg_hi:[0,0,1]
	v_pk_fma_f32 v[64:65], v[56:57], v[160:161], v[64:65]
	v_pk_fma_f32 v[62:63], v[54:55], v[158:159], v[62:63]
	v_cndmask_b32_e32 v57, v57, v61, vcc
	v_cndmask_b32_e32 v56, v56, v60, vcc
	v_cndmask_b32_e32 v55, v55, v59, vcc
	v_cndmask_b32_e32 v54, v54, v58, vcc
	v_cndmask_b32_e32 v53, v53, v65, vcc
	v_cndmask_b32_e32 v52, v52, v64, vcc
	v_cndmask_b32_e32 v51, v51, v63, vcc
	v_cndmask_b32_e32 v50, v50, v62, vcc
	v_pk_mul_f32 v[58:59], v[56:57], s[28:29] op_sel_hi:[1,0]
	v_pk_mul_f32 v[60:61], v[54:55], s[28:29] op_sel_hi:[1,0]
	v_pk_mul_f32 v[62:63], v[52:53], s[28:29] op_sel_hi:[1,0]
	v_pk_mul_f32 v[64:65], v[50:51], s[28:29] op_sel_hi:[1,0]
	v_cndmask_b32_e64 v56, v56, v58, s[44:45]
	v_cndmask_b32_e64 v57, v57, v59, s[44:45]
	v_cndmask_b32_e64 v54, v54, v60, s[44:45]
	v_cndmask_b32_e64 v55, v55, v61, s[44:45]
	v_cndmask_b32_e64 v58, v52, v62, s[44:45]
	v_cndmask_b32_e64 v53, v53, v63, s[44:45]
	v_cndmask_b32_e64 v52, v50, v64, s[44:45]
	v_cndmask_b32_e64 v59, v51, v65, s[44:45]
	v_cvt_pk_bf16_f32 v50, v54, v55
	v_cvt_pk_bf16_f32 v51, v56, v57
	v_cvt_pk_bf16_f32 v52, v52, v59
	v_cvt_pk_bf16_f32 v53, v58, v53
	ds_bpermute_b32 v50, v248, v50
	ds_bpermute_b32 v51, v248, v51
	ds_bpermute_b32 v52, v248, v52
	ds_bpermute_b32 v53, v248, v53
	v_lshl_add_u64 v[254:255], v[100:101], 0, v[252:253]
	s_waitcnt lgkmcnt(0)
	global_store_dwordx4 v[254:255], v[50:53], off offset:256
	v_pk_add_f32 v[44:45], v[44:45], v[92:93]
	v_pk_add_f32 v[42:43], v[42:43], v[90:91]
	v_mad_u64_u32 v[50:51], s[0:1], v98, s85, v[102:103]
	v_mov_b32_e32 v52, v51
	v_mad_u64_u32 v[52:53], s[0:1], v99, s85, v[52:53]
	v_pk_add_f32 v[48:49], v[48:49], v[96:97]
	v_pk_add_f32 v[46:47], v[46:47], v[94:95]
	v_pk_mul_f32 v[54:55], v[44:45], v[148:149]
	v_pk_mul_f32 v[56:57], v[42:43], v[150:151]
	v_pk_mul_f32 v[58:59], v[44:45], v[152:153]
	v_mov_b32_e32 v51, v52
	v_pk_mul_f32 v[52:53], v[42:43], v[146:147]
	v_pk_fma_f32 v[54:55], v[48:49], v[152:153], v[54:55] neg_lo:[0,0,1] neg_hi:[0,0,1]
	v_pk_fma_f32 v[58:59], v[48:49], v[148:149], v[58:59]
	v_pk_fma_f32 v[56:57], v[46:47], v[146:147], v[56:57]
	v_pk_fma_f32 v[52:53], v[46:47], v[150:151], v[52:53] neg_lo:[0,0,1] neg_hi:[0,0,1]
	v_cndmask_b32_e64 v49, v49, v55, s[40:41]
	v_cndmask_b32_e64 v48, v48, v54, s[40:41]
	v_cndmask_b32_e64 v45, v45, v59, s[40:41]
	v_cndmask_b32_e64 v44, v44, v58, s[40:41]
	v_cndmask_b32_e64 v43, v43, v57, s[40:41]
	v_cndmask_b32_e64 v42, v42, v56, s[40:41]
	v_cndmask_b32_e64 v47, v47, v53, s[40:41]
	v_cndmask_b32_e64 v46, v46, v52, s[40:41]
	v_pk_mul_f32 v[52:53], v[48:49], s[28:29] op_sel_hi:[1,0]
	v_pk_mul_f32 v[56:57], v[44:45], s[28:29] op_sel_hi:[1,0]
	v_pk_mul_f32 v[58:59], v[42:43], s[28:29] op_sel_hi:[1,0]
	v_pk_mul_f32 v[54:55], v[46:47], s[28:29] op_sel_hi:[1,0]
	v_cndmask_b32_e64 v48, v48, v52, s[42:43]
	v_cndmask_b32_e64 v52, v44, v56, s[42:43]
	v_cndmask_b32_e64 v45, v45, v57, s[42:43]
	v_cndmask_b32_e64 v44, v42, v58, s[42:43]
	v_lshl_add_u64 v[50:51], v[50:51], 0, v[186:187]
	v_cndmask_b32_e64 v49, v49, v53, s[42:43]
	v_cndmask_b32_e64 v46, v46, v54, s[42:43]
	v_cndmask_b32_e64 v47, v47, v55, s[42:43]
	v_cndmask_b32_e64 v53, v43, v59, s[42:43]
	v_cvt_pk_bf16_f32 v42, v46, v47
	v_cvt_pk_bf16_f32 v43, v48, v49
	v_cvt_pk_bf16_f32 v44, v44, v53
	v_cvt_pk_bf16_f32 v45, v52, v45
	v_pk_add_f32 v[36:37], v[36:37], v[76:77]
	v_pk_add_f32 v[34:35], v[34:35], v[74:75]
	ds_bpermute_b32 v42, v248, v42
	ds_bpermute_b32 v43, v248, v43
	ds_bpermute_b32 v44, v248, v44
	ds_bpermute_b32 v45, v248, v45
	v_lshl_add_u64 v[254:255], v[50:51], 0, v[252:253]
	s_waitcnt lgkmcnt(0)
	global_store_dwordx4 v[254:255], v[42:45], off
	v_pk_add_f32 v[40:41], v[40:41], v[80:81]
	v_pk_add_f32 v[38:39], v[38:39], v[78:79]
	v_pk_mul_f32 v[44:45], v[36:37], v[148:149]
	v_pk_mul_f32 v[46:47], v[34:35], v[150:151]
	v_pk_mul_f32 v[48:49], v[36:37], v[152:153]
	v_pk_mul_f32 v[42:43], v[34:35], v[146:147]
	v_pk_fma_f32 v[44:45], v[40:41], v[152:153], v[44:45] neg_lo:[0,0,1] neg_hi:[0,0,1]
	v_pk_fma_f32 v[48:49], v[40:41], v[148:149], v[48:49]
	v_pk_fma_f32 v[46:47], v[38:39], v[146:147], v[46:47]
	v_pk_fma_f32 v[42:43], v[38:39], v[150:151], v[42:43] neg_lo:[0,0,1] neg_hi:[0,0,1]
	v_cndmask_b32_e32 v41, v41, v45, vcc
	v_cndmask_b32_e32 v40, v40, v44, vcc
	v_cndmask_b32_e32 v37, v37, v49, vcc
	v_cndmask_b32_e32 v36, v36, v48, vcc
	v_cndmask_b32_e32 v35, v35, v47, vcc
	v_cndmask_b32_e32 v34, v34, v46, vcc
	v_cndmask_b32_e32 v39, v39, v43, vcc
	v_cndmask_b32_e32 v38, v38, v42, vcc
	v_pk_mul_f32 v[42:43], v[40:41], s[28:29] op_sel_hi:[1,0]
	v_pk_mul_f32 v[46:47], v[36:37], s[28:29] op_sel_hi:[1,0]
	v_pk_mul_f32 v[48:49], v[34:35], s[28:29] op_sel_hi:[1,0]
	v_pk_mul_f32 v[44:45], v[38:39], s[28:29] op_sel_hi:[1,0]
	v_cndmask_b32_e64 v40, v40, v42, s[44:45]
	v_cndmask_b32_e64 v42, v36, v46, s[44:45]
	v_cndmask_b32_e64 v37, v37, v47, s[44:45]
	v_cndmask_b32_e64 v36, v34, v48, s[44:45]
	v_cndmask_b32_e64 v41, v41, v43, s[44:45]
	v_cndmask_b32_e64 v38, v38, v44, s[44:45]
	v_cndmask_b32_e64 v39, v39, v45, s[44:45]
	v_cndmask_b32_e64 v43, v35, v49, s[44:45]
	v_cvt_pk_bf16_f32 v34, v38, v39
	v_cvt_pk_bf16_f32 v35, v40, v41
	v_cvt_pk_bf16_f32 v36, v36, v43
	v_cvt_pk_bf16_f32 v37, v42, v37
	ds_bpermute_b32 v34, v248, v34
	ds_bpermute_b32 v35, v248, v35
	ds_bpermute_b32 v36, v248, v36
	ds_bpermute_b32 v37, v248, v37
	v_lshl_add_u64 v[254:255], v[50:51], 0, v[252:253]
	s_waitcnt lgkmcnt(0)
; __device__ __forceinline__ unsigned cvt_pk_bf16(float lo, float hi) { unsigned r; asm volatile("v_cvt_pk_bf16_f32 %0, %1, %2" : "=v"(r) : "v"(lo), "v"(hi)); return r; }
;     __device__ __forceinline__ void operator()(const f32x4 (&acc)[2][2][4][2], const Unit& u, int wr, int wc, int fr, int fq) const {
;     ...
;             if (rot_wave && fq < 2) {
; #pragma unroll
;                 for (int mm = 0; mm < 2; ++mm) { const float* cr = cs + (size_t)(row0 + ai * HALF + (2 * mh + mm) * 16) * 16 + 4 * fq;
;                     cc[mm][0] = *(const f32x4*)(cr); cc[mm][1] = *(const f32x4*)(cr + 8); }
;             }
; #pragma unroll
;             for (int mm = 0; mm < 2; ++mm) {
;                 const int m = 2 * mh + mm;
;                 const int row = row0 + ai * HALF + m * 16;
;                 bf16_t* rowp = O + (size_t)row * INW + col0;
; #pragma unroll
;                 for (int bj = 0; bj < 2; ++bj) {
;                     f32x4 v0 = acc[ai][bj][m][0] + bv[bj][0], v1 = acc[ai][bj][m][1] + bv[bj][1];
;                     const int cb = colt + bj * HALF;
;                     if (rot_wave && cb < 640) {
;                         const f32x4 t1 = v0, t2 = v1;
;                         v0 = t1 * cc[mm][0] - t2 * cc[mm][1]; v1 = t2 * cc[mm][0] + t1 * cc[mm][1];
;                     }
;                     if (cb < 512) { v0 = v0 * 0.125f; v1 = v1 * 0.125f; }
;                     u32x4 w; w.x = cvt_pk_bf16(v0[0], v0[1]); w.y = cvt_pk_bf16(v0[2], v0[3]); w.z = cvt_pk_bf16(v1[0], v1[1]); w.w = cvt_pk_bf16(v1[2], v1[3]);
;                     *(u32x4*)(rowp + bj * HALF) = w;
	global_store_dwordx4 v[254:255], v[34:37], off offset:256
	v_add_u32_e32 v50, 0xb0, v188
	v_ashrrev_i32_e32 v51, 31, v50
	v_add_u32_e32 v52, 0xa0, v188
	v_ashrrev_i32_e32 v53, 31, v52
	v_pk_add_f32 v[28:29], v[28:29], v[92:93]
	v_pk_add_f32 v[26:27], v[26:27], v[90:91]
	v_pk_add_f32 v[32:33], v[32:33], v[96:97]
	v_pk_add_f32 v[30:31], v[30:31], v[94:95]
	s_waitcnt vmcnt(4)
	v_pk_mul_f32 v[58:59], v[28:29], v[234:235]
	v_pk_mul_f32 v[60:61], v[26:27], v[228:229]
	v_pk_mul_f32 v[62:63], v[28:29], v[230:231]
	v_pk_mul_f32 v[56:57], v[26:27], v[232:233]
	v_pk_fma_f32 v[58:59], v[32:33], v[230:231], v[58:59] neg_lo:[0,0,1] neg_hi:[0,0,1]
	v_pk_fma_f32 v[62:63], v[32:33], v[234:235], v[62:63]
	v_pk_fma_f32 v[60:61], v[30:31], v[232:233], v[60:61]
	v_pk_fma_f32 v[56:57], v[30:31], v[228:229], v[56:57] neg_lo:[0,0,1] neg_hi:[0,0,1]
	v_cndmask_b32_e64 v33, v33, v59, s[40:41]
	v_cndmask_b32_e64 v32, v32, v58, s[40:41]
	v_cndmask_b32_e64 v29, v29, v63, s[40:41]
	v_cndmask_b32_e64 v28, v28, v62, s[40:41]
	v_cndmask_b32_e64 v27, v27, v61, s[40:41]
	v_cndmask_b32_e64 v26, v26, v60, s[40:41]
	v_mov_b64_e32 v[54:55], s[74:75]
	v_cndmask_b32_e64 v31, v31, v57, s[40:41]
	v_cndmask_b32_e64 v30, v30, v56, s[40:41]
	v_pk_mul_f32 v[56:57], v[32:33], s[28:29] op_sel_hi:[1,0]
	v_pk_mul_f32 v[60:61], v[28:29], s[28:29] op_sel_hi:[1,0]
	v_pk_mul_f32 v[62:63], v[26:27], s[28:29] op_sel_hi:[1,0]
	v_mad_i64_i32 v[52:53], s[0:1], v52, s85, v[54:55]
	v_pk_mul_f32 v[58:59], v[30:31], s[28:29] op_sel_hi:[1,0]
	v_cndmask_b32_e64 v32, v32, v56, s[42:43]
	v_cndmask_b32_e64 v56, v28, v60, s[42:43]
	v_cndmask_b32_e64 v29, v29, v61, s[42:43]
	v_cndmask_b32_e64 v28, v26, v62, s[42:43]
	v_lshl_add_u64 v[52:53], v[52:53], 0, v[186:187]
	v_cndmask_b32_e64 v33, v33, v57, s[42:43]
	v_cndmask_b32_e64 v30, v30, v58, s[42:43]
	v_cndmask_b32_e64 v31, v31, v59, s[42:43]
	v_cndmask_b32_e64 v57, v27, v63, s[42:43]
	v_cvt_pk_bf16_f32 v26, v30, v31
	v_cvt_pk_bf16_f32 v27, v32, v33
	v_cvt_pk_bf16_f32 v28, v28, v57
	v_cvt_pk_bf16_f32 v29, v56, v29
	v_pk_add_f32 v[20:21], v[20:21], v[76:77]
	v_pk_add_f32 v[18:19], v[18:19], v[74:75]
	ds_bpermute_b32 v26, v248, v26
	ds_bpermute_b32 v27, v248, v27
	ds_bpermute_b32 v28, v248, v28
	ds_bpermute_b32 v29, v248, v29
	v_lshl_add_u64 v[254:255], v[52:53], 0, v[252:253]
	s_waitcnt lgkmcnt(0)
	global_store_dwordx4 v[254:255], v[26:29], off
	v_pk_add_f32 v[24:25], v[24:25], v[80:81]
	v_pk_add_f32 v[22:23], v[22:23], v[78:79]
	v_pk_mul_f32 v[26:27], v[18:19], v[232:233]
	v_pk_mul_f32 v[28:29], v[20:21], v[234:235]
	v_pk_mul_f32 v[30:31], v[18:19], v[228:229]
	v_pk_mul_f32 v[32:33], v[20:21], v[230:231]
	v_pk_fma_f32 v[28:29], v[24:25], v[230:231], v[28:29] neg_lo:[0,0,1] neg_hi:[0,0,1]
	v_pk_fma_f32 v[26:27], v[22:23], v[228:229], v[26:27] neg_lo:[0,0,1] neg_hi:[0,0,1]
	v_pk_fma_f32 v[32:33], v[24:25], v[234:235], v[32:33]
	v_pk_fma_f32 v[30:31], v[22:23], v[232:233], v[30:31]
	v_cndmask_b32_e32 v25, v25, v29, vcc
	v_cndmask_b32_e32 v24, v24, v28, vcc
	v_cndmask_b32_e32 v23, v23, v27, vcc
	v_cndmask_b32_e32 v22, v22, v26, vcc
	v_cndmask_b32_e32 v21, v21, v33, vcc
	v_cndmask_b32_e32 v20, v20, v32, vcc
	v_cndmask_b32_e32 v19, v19, v31, vcc
	v_cndmask_b32_e32 v18, v18, v30, vcc
	v_pk_mul_f32 v[26:27], v[24:25], s[28:29] op_sel_hi:[1,0]
	v_pk_mul_f32 v[28:29], v[22:23], s[28:29] op_sel_hi:[1,0]
	v_pk_mul_f32 v[30:31], v[20:21], s[28:29] op_sel_hi:[1,0]
	v_pk_mul_f32 v[32:33], v[18:19], s[28:29] op_sel_hi:[1,0]
	v_cndmask_b32_e64 v24, v24, v26, s[44:45]
	v_cndmask_b32_e64 v25, v25, v27, s[44:45]
	v_cndmask_b32_e64 v22, v22, v28, s[44:45]
	v_cndmask_b32_e64 v23, v23, v29, s[44:45]
	v_cndmask_b32_e64 v26, v20, v30, s[44:45]
	v_cndmask_b32_e64 v21, v21, v31, s[44:45]
	v_cndmask_b32_e64 v20, v18, v32, s[44:45]
	v_cndmask_b32_e64 v27, v19, v33, s[44:45]
	v_cvt_pk_bf16_f32 v18, v22, v23
	v_cvt_pk_bf16_f32 v19, v24, v25
	v_cvt_pk_bf16_f32 v20, v20, v27
	v_cvt_pk_bf16_f32 v21, v26, v21
	ds_bpermute_b32 v18, v248, v18
	ds_bpermute_b32 v19, v248, v19
	ds_bpermute_b32 v20, v248, v20
	ds_bpermute_b32 v21, v248, v21
	v_lshl_add_u64 v[254:255], v[52:53], 0, v[252:253]
	s_waitcnt lgkmcnt(0)
; __device__ __forceinline__ unsigned cvt_pk_bf16(float lo, float hi) { unsigned r; asm volatile("v_cvt_pk_bf16_f32 %0, %1, %2" : "=v"(r) : "v"(lo), "v"(hi)); return r; }
; #define PG8_BAR __builtin_amdgcn_s_barrier()
;     ...
;         if (!has_next) break;
; #pragma unroll
;         for (int a = 0; a < 2; ++a)
; #pragma unroll
;             for (int b = 0; b < 2; ++b)
; #pragma unroll
;                 for (int m = 0; m < 4; ++m)
; #pragma unroll
;                     for (int n = 0; n < 2; ++n) acc[a][b][m][n] = (f32x4){0.f, 0.f, 0.f, 0.f};
;         cur = nxt; cA = nA; cB = nB; ++ui;
;         if constexpr (ALIGN_EPI) { if (wr == 1) PG8_BAR; }
;     __device__ __forceinline__ void operator()(const f32x4 (&acc)[2][2][4][2], const Unit& u, int wr, int wc, int fr, int fq) const {
;     ...
;             for (int mm = 0; mm < 2; ++mm) {
;                 const int m = 2 * mh + mm;
;                 const int row = row0 + ai * HALF + m * 16;
;                 bf16_t* rowp = O + (size_t)row * INW + col0;
; #pragma unroll
;                 for (int bj = 0; bj < 2; ++bj) {
;                     f32x4 v0 = acc[ai][bj][m][0] + bv[bj][0], v1 = acc[ai][bj][m][1] + bv[bj][1];
;                     const int cb = colt + bj * HALF;
;                     if (rot_wave && cb < 640) {
;                         const f32x4 t1 = v0, t2 = v1;
;                         v0 = t1 * cc[mm][0] - t2 * cc[mm][1]; v1 = t2 * cc[mm][0] + t1 * cc[mm][1];
;                     }
;                     if (cb < 512) { v0 = v0 * 0.125f; v1 = v1 * 0.125f; }
;                     u32x4 w; w.x = cvt_pk_bf16(v0[0], v0[1]); w.y = cvt_pk_bf16(v0[2], v0[3]); w.z = cvt_pk_bf16(v1[0], v1[1]); w.w = cvt_pk_bf16(v1[2], v1[3]);
;                     *(u32x4*)(rowp + bj * HALF) = w;
;                 }
;             }
	global_store_dwordx4 v[254:255], v[18:21], off offset:256
	v_pk_add_f32 v[12:13], v[12:13], v[92:93]
	v_pk_add_f32 v[10:11], v[10:11], v[90:91]
	v_mad_u64_u32 v[18:19], s[0:1], v50, s85, v[54:55]
	v_mov_b32_e32 v20, v19
	v_mad_u64_u32 v[20:21], s[0:1], v51, s85, v[20:21]
	v_pk_add_f32 v[16:17], v[16:17], v[96:97]
	v_pk_add_f32 v[14:15], v[14:15], v[94:95]
	v_pk_mul_f32 v[22:23], v[12:13], v[222:223]
	v_pk_mul_f32 v[24:25], v[10:11], v[224:225]
	v_pk_mul_f32 v[26:27], v[12:13], v[226:227]
	v_mov_b32_e32 v19, v20
	v_pk_mul_f32 v[20:21], v[10:11], v[220:221]
	v_pk_fma_f32 v[22:23], v[16:17], v[226:227], v[22:23] neg_lo:[0,0,1] neg_hi:[0,0,1]
	v_pk_fma_f32 v[26:27], v[16:17], v[222:223], v[26:27]
	v_pk_fma_f32 v[24:25], v[14:15], v[220:221], v[24:25]
	v_pk_fma_f32 v[20:21], v[14:15], v[224:225], v[20:21] neg_lo:[0,0,1] neg_hi:[0,0,1]
	v_cndmask_b32_e64 v17, v17, v23, s[40:41]
	v_cndmask_b32_e64 v16, v16, v22, s[40:41]
	v_cndmask_b32_e64 v13, v13, v27, s[40:41]
	v_cndmask_b32_e64 v12, v12, v26, s[40:41]
	v_cndmask_b32_e64 v11, v11, v25, s[40:41]
	v_cndmask_b32_e64 v10, v10, v24, s[40:41]
	v_cndmask_b32_e64 v15, v15, v21, s[40:41]
	v_cndmask_b32_e64 v14, v14, v20, s[40:41]
	v_pk_mul_f32 v[20:21], v[16:17], s[28:29] op_sel_hi:[1,0]
	v_pk_mul_f32 v[24:25], v[12:13], s[28:29] op_sel_hi:[1,0]
	v_pk_mul_f32 v[26:27], v[10:11], s[28:29] op_sel_hi:[1,0]
	v_pk_mul_f32 v[22:23], v[14:15], s[28:29] op_sel_hi:[1,0]
	v_cndmask_b32_e64 v16, v16, v20, s[42:43]
	v_cndmask_b32_e64 v20, v12, v24, s[42:43]
	v_cndmask_b32_e64 v13, v13, v25, s[42:43]
	v_cndmask_b32_e64 v12, v10, v26, s[42:43]
	v_lshl_add_u64 v[18:19], v[18:19], 0, v[186:187]
	v_cndmask_b32_e64 v17, v17, v21, s[42:43]
	v_cndmask_b32_e64 v14, v14, v22, s[42:43]
	v_cndmask_b32_e64 v15, v15, v23, s[42:43]
	v_cndmask_b32_e64 v21, v11, v27, s[42:43]
	v_cvt_pk_bf16_f32 v10, v14, v15
	v_cvt_pk_bf16_f32 v11, v16, v17
	v_cvt_pk_bf16_f32 v12, v12, v21
	v_cvt_pk_bf16_f32 v13, v20, v13
	v_pk_add_f32 v[4:5], v[4:5], v[76:77]
	v_pk_add_f32 v[2:3], v[2:3], v[74:75]
	ds_bpermute_b32 v10, v248, v10
	ds_bpermute_b32 v11, v248, v11
	ds_bpermute_b32 v12, v248, v12
	ds_bpermute_b32 v13, v248, v13
	v_lshl_add_u64 v[254:255], v[18:19], 0, v[252:253]
	s_waitcnt lgkmcnt(0)
	global_store_dwordx4 v[254:255], v[10:13], off
	v_pk_add_f32 v[8:9], v[8:9], v[80:81]
	v_pk_add_f32 v[6:7], v[6:7], v[78:79]
	v_pk_mul_f32 v[12:13], v[4:5], v[222:223]
	v_pk_mul_f32 v[14:15], v[2:3], v[224:225]
	v_pk_mul_f32 v[16:17], v[4:5], v[226:227]
	v_pk_mul_f32 v[10:11], v[2:3], v[220:221]
	v_pk_fma_f32 v[12:13], v[8:9], v[226:227], v[12:13] neg_lo:[0,0,1] neg_hi:[0,0,1]
	v_pk_fma_f32 v[16:17], v[8:9], v[222:223], v[16:17]
	v_pk_fma_f32 v[14:15], v[6:7], v[220:221], v[14:15]
	v_pk_fma_f32 v[10:11], v[6:7], v[224:225], v[10:11] neg_lo:[0,0,1] neg_hi:[0,0,1]
	v_cndmask_b32_e32 v9, v9, v13, vcc
	v_cndmask_b32_e32 v8, v8, v12, vcc
	v_cndmask_b32_e32 v5, v5, v17, vcc
	v_cndmask_b32_e32 v4, v4, v16, vcc
	v_cndmask_b32_e32 v3, v3, v15, vcc
	v_cndmask_b32_e32 v2, v2, v14, vcc
	v_cndmask_b32_e32 v7, v7, v11, vcc
	v_cndmask_b32_e32 v6, v6, v10, vcc
	v_pk_mul_f32 v[10:11], v[8:9], s[28:29] op_sel_hi:[1,0]
	v_pk_mul_f32 v[14:15], v[4:5], s[28:29] op_sel_hi:[1,0]
	v_pk_mul_f32 v[16:17], v[2:3], s[28:29] op_sel_hi:[1,0]
	v_pk_mul_f32 v[12:13], v[6:7], s[28:29] op_sel_hi:[1,0]
	v_cndmask_b32_e64 v8, v8, v10, s[44:45]
	v_cndmask_b32_e64 v10, v4, v14, s[44:45]
	v_cndmask_b32_e64 v5, v5, v15, s[44:45]
	v_cndmask_b32_e64 v4, v2, v16, s[44:45]
	s_andn2_b64 vcc, exec, s[38:39]
	s_mov_b64 s[0:1], -1
	v_cndmask_b32_e64 v9, v9, v11, s[44:45]
	v_cndmask_b32_e64 v6, v6, v12, s[44:45]
	v_cndmask_b32_e64 v7, v7, v13, s[44:45]
	v_cndmask_b32_e64 v11, v3, v17, s[44:45]
	v_cvt_pk_bf16_f32 v2, v6, v7
	v_cvt_pk_bf16_f32 v3, v8, v9
	v_cvt_pk_bf16_f32 v4, v4, v11
	v_cvt_pk_bf16_f32 v5, v10, v5
	ds_bpermute_b32 v2, v248, v2
	ds_bpermute_b32 v3, v248, v3
	ds_bpermute_b32 v4, v248, v4
	ds_bpermute_b32 v5, v248, v5
	v_lshl_add_u64 v[254:255], v[18:19], 0, v[252:253]
	s_waitcnt lgkmcnt(0)
	global_store_dwordx4 v[254:255], v[2:5], off offset:256
	s_cbranch_vccnz .LBB0_182
	s_andn2_b64 vcc, exec, s[20:21]
	s_cbranch_vccnz .LBB0_181
	s_barrier
	s_branch .LBB0_181
